# attention items: static s_setprio 1 for waves 4-7 during the tile loop
# speedup vs baseline: 1.0019x; 1.0019x over previous
.LBB0_561:
	s_or_b64 exec, exec, s[8:9]
	s_mov_b64 s[8:9], 0x20000
	s_lshl_b32 s7, s14, 6
	v_lshl_add_u64 v[140:141], v[18:19], 0, s[8:9]
	s_lshl_b32 s12, s12, 16
	v_readlane_b32 s8, v254, 50
	s_add_u32 s8, s8, s12
	v_readlane_b32 s9, v254, 51
	s_addc_u32 s9, s9, 0
	s_add_u32 s8, s8, s13
	s_addc_u32 s9, s9, 0
	v_readlane_b32 s15, v254, 52
	s_add_u32 s12, s15, s12
	v_readlane_b32 s15, v254, 53
	s_addc_u32 s15, s15, 0
	s_add_u32 s12, s12, s13
	s_addc_u32 s13, s15, 0
	v_lshl_add_u64 v[18:19], v[24:25], 1, s[8:9]
	v_lshlrev_b64 v[22:23], 8, v[22:23]
	v_readlane_b32 s8, v254, 19
	v_lshl_add_u64 v[20:21], v[26:27], 1, s[12:13]
	v_lshl_add_u64 v[142:143], v[18:19], 0, v[22:23]
	v_lshlrev_b32_e32 v18, 8, v30
	v_mov_b32_e32 v19, v1
	v_mov_b32_e32 v42, v1
	v_mov_b32_e32 v43, v1
	v_mov_b32_e32 v44, v1
	v_mov_b32_e32 v45, v1
	v_readlane_b32 s9, v254, 20
	s_mov_b32 s8, 0x8000
	v_mul_u32_u24_e32 v158, 0x90, v32
	v_lshl_add_u64 v[144:145], v[20:21], 0, v[18:19]
	v_mov_b32_e32 v169, v168
	v_writelane_b32 v254, s8, 19
	v_mov_b64_e32 v[18:19], v[42:43]
	v_mov_b64_e32 v[48:49], v[44:45]
	v_mov_b64_e32 v[22:23], v[42:43]
	v_mov_b64_e32 v[38:39], v[42:43]
	v_mov_b64_e32 v[26:27], v[42:43]
	v_mov_b64_e32 v[34:35], v[42:43]
	v_mov_b64_e32 v[30:31], v[42:43]
	s_add_i32 s15, s0, 1
	s_add_i32 s16, s1, -2
	v_mov_b32_e32 v148, v1
	v_mov_b32_e32 v149, v1
	v_writelane_b32 v254, s9, 20
	s_movk_i32 s8, 0x200
	s_mov_b32 s19, 0
	v_mov_b64_e32 v[20:21], v[44:45]
	v_mov_b64_e32 v[46:47], v[42:43]
	v_mov_b64_e32 v[24:25], v[44:45]
	v_mov_b64_e32 v[40:41], v[44:45]
	v_mov_b64_e32 v[28:29], v[44:45]
	v_mov_b64_e32 v[36:37], v[44:45]
	v_mov_b64_e32 v[32:33], v[44:45]
	v_mov_b64_e32 v[146:147], v[168:169]
	s_waitcnt lgkmcnt(0)
	s_barrier
	v_readfirstlane_b32 s98, v163
	s_cmp_lt_u32 s98, 0x100
	s_cbranch_scc1 .Lpr_in0
	s_setprio 1
.Lpr_in0:
.LBB0_562:
	s_add_i32 s18, s19, 1
	s_bitcmp1_b32 s18, 0
	s_cselect_b32 s9, 0x4800, 0
	s_add_i32 s17, s9, 0
	v_add3_u32 v70, s17, v156, v157
	s_waitcnt vmcnt(0)
	ds_write_b128 v70, v[66:69]
	s_and_saveexec_b64 s[12:13], s[4:5]
	s_cbranch_execnz .LBB0_568
	s_or_b64 exec, exec, s[12:13]
	s_cmp_lg_u32 s16, s19
	s_cbranch_scc0 .LBB0_569

.LBB0_610:
	s_or_b64 exec, exec, s[12:13]
	s_lshl_b32 s12, s14, 7
	v_readlane_b32 s14, v254, 19
	v_readlane_b32 s15, v254, 20
	s_mov_b32 s17, s15
	s_or_b32 s16, s3, 0x6000
	s_lshl_b64 s[14:15], s[16:17], 10
	v_readlane_b32 s3, v254, 44
	s_add_u32 s3, s3, s14
	v_readlane_b32 s13, v254, 45
	s_addc_u32 s13, s13, s15
	s_lshl_b32 s14, s12, 1
	s_add_u32 s14, s3, s14
	s_mov_b32 s3, s17
	v_writelane_b32 v254, s2, 19
	v_mov_b32_e32 v27, v1
	s_addc_u32 s15, s13, 0
	v_writelane_b32 v254, s3, 20
	s_lshl_b64 s[16:17], s[16:17], 6
	v_readlane_b32 s3, v254, 46
	v_mov_b32_e32 v36, v32
	v_lshlrev_b32_e32 v46, 11, v54
	v_lshl_add_u64 v[158:159], v[28:29], 0, v[26:27]
	s_add_u32 s16, s3, s16
	v_readlane_b32 s3, v254, 47
	v_lshl_add_u64 v[28:29], v[36:37], 1, s[14:15]
	s_addc_u32 s17, s3, s17
	v_mov_b32_e32 v33, v1
	v_mov_b32_e32 v41, v1
	v_lshl_add_u64 v[28:29], v[28:29], 0, v[34:35]
	v_lshlrev_b32_e32 v34, 1, v46
	v_mov_b32_e32 v35, v1
	v_mov_b32_e32 v44, v40
	v_lshl_add_u64 v[26:27], v[32:33], 1, s[16:17]
	v_lshl_add_u64 v[32:33], v[40:41], 1, s[16:17]
	s_movk_i32 s16, 0xff80
	v_lshl_add_u64 v[34:35], s[14:15], 0, v[34:35]
	v_lshl_add_u64 v[36:37], v[44:45], 1, s[14:15]
	v_lshl_add_u64 v[26:27], v[26:27], 0, v[30:31]
	s_mov_b32 s17, -1
	v_lshl_add_u64 v[30:31], v[32:33], 0, v[38:39]
	v_lshl_add_u64 v[34:35], v[48:49], 1, v[34:35]
	v_mul_u32_u24_e32 v187, 0xd0, v54
	v_mul_u32_u24_e32 v151, 0x90, v54
	v_lshl_add_u64 v[26:27], v[26:27], 0, s[16:17]
	v_lshl_add_u64 v[30:31], v[30:31], 0, s[16:17]
	v_lshl_add_u64 v[32:33], v[36:37], 0, v[42:43]
	v_lshl_add_u64 v[176:177], v[34:35], 0, s[92:93]
	v_mov_b32_e32 v34, 0x8000
	v_mov_b32_e32 v54, v1
	v_mov_b32_e32 v55, v1
	v_cndmask_b32_e32 v194, v216, v34, vcc
	v_cndmask_b32_e32 v179, v27, v29, vcc
	v_cndmask_b32_e32 v178, v26, v28, vcc
	v_cndmask_b32_e64 v195, v216, v34, s[8:9]
	v_cndmask_b32_e64 v181, v31, v33, s[8:9]
	v_cndmask_b32_e64 v180, v30, v32, s[8:9]
	v_mov_b32_e32 v169, v168
	v_mov_b32_e32 v56, v1
	v_mov_b32_e32 v57, v1
	v_mov_b64_e32 v[26:27], v[54:55]
	v_mov_b64_e32 v[50:51], v[54:55]
	v_mov_b64_e32 v[30:31], v[54:55]
	v_mov_b64_e32 v[46:47], v[54:55]
	v_mov_b64_e32 v[34:35], v[54:55]
	v_mov_b64_e32 v[42:43], v[54:55]
	v_mov_b64_e32 v[38:39], v[54:55]
	v_ashrrev_i32_e32 v149, 31, v148
	v_ashrrev_i32_e32 v147, 31, v146
	s_add_i32 s0, s0, 1
	s_add_i32 s1, s1, -2
	v_mov_b32_e32 v182, v1
	v_mov_b32_e32 v183, v1
	s_mov_b32 s14, 0
	v_mov_b64_e32 v[28:29], v[56:57]
	v_mov_b64_e32 v[52:53], v[56:57]
	v_mov_b64_e32 v[32:33], v[56:57]
	v_mov_b64_e32 v[48:49], v[56:57]
	v_mov_b64_e32 v[36:37], v[56:57]
	v_mov_b64_e32 v[44:45], v[56:57]
	v_mov_b64_e32 v[40:41], v[56:57]
	v_mov_b64_e32 v[160:161], v[168:169]
	s_waitcnt lgkmcnt(0)
	s_barrier
	v_readfirstlane_b32 s98, v163
	s_cmp_lt_u32 s98, 0x100
	s_cbranch_scc1 .Lpr_in1
	s_setprio 1
.Lpr_in1:
.LBB0_611:
	s_add_i32 s13, s14, 1
	s_bitcmp1_b32 s13, 0
	s_cselect_b32 s3, 0x5800, 0
	s_add_i32 s3, s3, 0
	v_add3_u32 v82, s3, v190, v191
	s_waitcnt vmcnt(0)
	ds_write_b128 v82, v[78:81]
	s_and_saveexec_b64 s[8:9], s[4:5]
	s_cbranch_execnz .LBB0_619
	s_or_b64 exec, exec, s[8:9]
	s_and_saveexec_b64 s[8:9], s[6:7]
	s_cbranch_execnz .LBB0_620

.LBB0_645:
	s_setprio 0
	s_mov_b64 s[4:5], 0
	v_readlane_b32 s3, v255, 0
